# v25 + attention step: QK^T MFMAs issued accumulator-chained (all four k-steps of score block 0, then block 1) instead of alternating the two score blocks
# speedup vs baseline: 1.0039x; 1.0039x over previous
.Lat_mainloop:
.Lat_step_M1:
	v_add_u32_e32 v243, s16, v204
	ds_read_b64_tr_b16 v[214:215], v243 offset:24576
	ds_read_b64_tr_b16 v[216:217], v243 offset:25088
	v_mfma_f32_32x32x16_bf16 v[112:127], v[176:179], v[144:147], v[64:79]
	v_add_f32_e32 v245, v80, v81
	v_add_f32_e32 v246, v82, v83
	v_add_f32_e32 v245, v84, v245
	v_add_f32_e32 v246, v85, v246
	v_cvt_pk_bf16_f32 v160, v80, v81
	v_cvt_pk_bf16_f32 v161, v82, v83
	ds_read_b64_tr_b16 v[80:81], v243 offset:28672
	ds_read_b64_tr_b16 v[82:83], v243 offset:29184
	v_mfma_f32_32x32x16_bf16 v[112:127], v[184:187], v[148:151], v[112:127]
	v_add_f32_e32 v245, v86, v245
	v_add_f32_e32 v246, v87, v246
	v_add_f32_e32 v245, v88, v245
	v_add_f32_e32 v246, v89, v246
	v_cvt_pk_bf16_f32 v162, v84, v85
	v_cvt_pk_bf16_f32 v163, v86, v87
	ds_read_b64_tr_b16 v[84:85], v243 offset:25600
	ds_read_b64_tr_b16 v[86:87], v243 offset:26112
	v_mfma_f32_32x32x16_bf16 v[112:127], v[192:195], v[152:155], v[112:127]
	v_add_f32_e32 v245, v90, v245
	v_add_f32_e32 v246, v91, v246
	v_add_f32_e32 v245, v92, v245
	v_add_f32_e32 v246, v93, v246
	v_cvt_pk_bf16_f32 v164, v88, v89
	v_cvt_pk_bf16_f32 v165, v90, v91
	ds_read_b64_tr_b16 v[88:89], v243 offset:29696
	ds_read_b64_tr_b16 v[90:91], v243 offset:30208
	v_mfma_f32_32x32x16_bf16 v[112:127], v[200:203], v[156:159], v[112:127]
	v_add_f32_e32 v245, v94, v245
	v_add_f32_e32 v246, v95, v246
	v_add_f32_e32 v245, v96, v245
	v_add_f32_e32 v246, v97, v246
	v_cvt_pk_bf16_f32 v166, v92, v93
	v_cvt_pk_bf16_f32 v167, v94, v95
	ds_read_b64_tr_b16 v[92:93], v243 offset:26624
	ds_read_b64_tr_b16 v[94:95], v243 offset:27136
	v_mfma_f32_32x32x16_bf16 v[128:143], v[180:183], v[144:147], v[64:79]
	v_add_f32_e32 v245, v98, v245
	v_add_f32_e32 v246, v99, v246
	v_add_f32_e32 v245, v100, v245
	v_add_f32_e32 v246, v101, v246
	v_cvt_pk_bf16_f32 v168, v96, v97
	v_cvt_pk_bf16_f32 v169, v98, v99
	ds_read_b64_tr_b16 v[96:97], v243 offset:30720
	ds_read_b64_tr_b16 v[98:99], v243 offset:31232
	v_mfma_f32_32x32x16_bf16 v[128:143], v[188:191], v[148:151], v[128:143]
	v_add_f32_e32 v245, v102, v245
	v_add_f32_e32 v246, v103, v246
	v_add_f32_e32 v245, v104, v245
	v_add_f32_e32 v246, v105, v246
	v_cvt_pk_bf16_f32 v170, v100, v101
	v_cvt_pk_bf16_f32 v171, v102, v103
	ds_read_b64_tr_b16 v[100:101], v243 offset:27648
	ds_read_b64_tr_b16 v[102:103], v243 offset:28160
	v_mfma_f32_32x32x16_bf16 v[128:143], v[196:199], v[152:155], v[128:143]
	v_add_f32_e32 v245, v106, v245
	v_add_f32_e32 v246, v107, v246
	v_add_f32_e32 v245, v108, v245
	v_add_f32_e32 v246, v109, v246
	v_cvt_pk_bf16_f32 v172, v104, v105
	v_cvt_pk_bf16_f32 v173, v106, v107
	ds_read_b64_tr_b16 v[104:105], v243 offset:31744
	ds_read_b64_tr_b16 v[106:107], v243 offset:32256
	v_mfma_f32_32x32x16_bf16 v[128:143], v[206:209], v[156:159], v[128:143]
	v_add_f32_e32 v245, v110, v245
	v_add_f32_e32 v246, v111, v246
	v_add_f32_e32 v245, v245, v246
	v_cvt_pk_bf16_f32 v174, v108, v109
	v_cvt_pk_bf16_f32 v175, v110, v111
	v_add_f32_e32 v211, v211, v245
	v_add_u32_e32 v244, s18, v219
	s_waitcnt lgkmcnt(8)
	v_mfma_f32_32x32x16_bf16 v[0:15], v[160:163], v[214:217], v[0:15]
	v_max3_f32 v246, v112, v113, v114
	v_max3_f32 v247, v115, v116, v117
	ds_read_b64_tr_b16 v[214:215], v243 offset:49152
	ds_read_b64_tr_b16 v[216:217], v243 offset:49664
	v_mfma_f32_32x32x16_bf16 v[16:31], v[160:163], v[80:83], v[16:31]
	s_add_i32 m0, s17, s54
	v_max3_f32 v246, v246, v118, v119
	v_max3_f32 v247, v247, v120, v121
	v_max3_f32 v246, v246, v122, v123
	v_max3_f32 v247, v247, v124, v125
	ds_read_b64_tr_b16 v[80:81], v243 offset:53248
	ds_read_b64_tr_b16 v[82:83], v243 offset:53760
	global_load_lds_dwordx4 v222, s[0:1]
	s_add_u32 s0, s0, 0x20000
	s_addc_u32 s1, s1, 0
	v_mfma_f32_32x32x16_bf16 v[0:15], v[164:167], v[84:87], v[0:15]
	s_add_i32 s21, s18, s54
	s_add_i32 m0, s21, 0x6000
	v_max3_f32 v246, v246, v126, v127
	v_max3_f32 v247, v247, v128, v129
	v_max3_f32 v246, v246, v130, v131
	v_max3_f32 v247, v247, v132, v133
	ds_read_b64_tr_b16 v[84:85], v243 offset:50176
	ds_read_b64_tr_b16 v[86:87], v243 offset:50688
	global_load_lds_dwordx4 v223, s[4:5]
	v_mfma_f32_32x32x16_bf16 v[16:31], v[164:167], v[88:91], v[16:31]
	s_add_i32 m0, s21, 0xc000
	v_max3_f32 v246, v246, v134, v135
	v_max3_f32 v247, v247, v136, v137
	v_max3_f32 v246, v246, v138, v139
	v_max3_f32 v247, v247, v140, v141
	ds_read_b64_tr_b16 v[88:89], v243 offset:54272
	ds_read_b64_tr_b16 v[90:91], v243 offset:54784
	global_load_lds_dwordx4 v224, s[4:5]
	s_add_u32 s4, s4, 0x20000
	s_addc_u32 s5, s5, 0
	s_waitcnt lgkmcnt(8)
	v_mfma_f32_32x32x16_bf16 v[0:15], v[168:171], v[92:95], v[0:15]
	v_max3_f32 v246, v246, v142, v143
	v_max_f32_e32 v248, v246, v247
	ds_read_b64_tr_b16 v[92:93], v243 offset:51200
	ds_read_b64_tr_b16 v[94:95], v243 offset:51712
	v_cmp_lt_f32_e32 vcc, s87, v248
	s_cbranch_vccnz .Lat_rare_M1

.Lat_step_M2:
	v_add_u32_e32 v243, s16, v204
	ds_read_b64_tr_b16 v[214:215], v243 offset:24576
	ds_read_b64_tr_b16 v[216:217], v243 offset:25088
	v_mfma_f32_32x32x16_bf16 v[80:95], v[176:179], v[144:147], v[64:79]
	v_add_f32_e32 v245, v112, v113
	v_add_f32_e32 v246, v114, v115
	v_add_f32_e32 v245, v116, v245
	v_add_f32_e32 v246, v117, v246
	v_cvt_pk_bf16_f32 v160, v112, v113
	v_cvt_pk_bf16_f32 v161, v114, v115
	ds_read_b64_tr_b16 v[112:113], v243 offset:28672
	ds_read_b64_tr_b16 v[114:115], v243 offset:29184
	v_mfma_f32_32x32x16_bf16 v[80:95], v[184:187], v[148:151], v[80:95]
	v_add_f32_e32 v245, v118, v245
	v_add_f32_e32 v246, v119, v246
	v_add_f32_e32 v245, v120, v245
	v_add_f32_e32 v246, v121, v246
	v_cvt_pk_bf16_f32 v162, v116, v117
	v_cvt_pk_bf16_f32 v163, v118, v119
	ds_read_b64_tr_b16 v[116:117], v243 offset:25600
	ds_read_b64_tr_b16 v[118:119], v243 offset:26112
	v_mfma_f32_32x32x16_bf16 v[80:95], v[192:195], v[152:155], v[80:95]
	v_add_f32_e32 v245, v122, v245
	v_add_f32_e32 v246, v123, v246
	v_add_f32_e32 v245, v124, v245
	v_add_f32_e32 v246, v125, v246
	v_cvt_pk_bf16_f32 v164, v120, v121
	v_cvt_pk_bf16_f32 v165, v122, v123
	ds_read_b64_tr_b16 v[120:121], v243 offset:29696
	ds_read_b64_tr_b16 v[122:123], v243 offset:30208
	v_mfma_f32_32x32x16_bf16 v[80:95], v[200:203], v[156:159], v[80:95]
	v_add_f32_e32 v245, v126, v245
	v_add_f32_e32 v246, v127, v246
	v_add_f32_e32 v245, v128, v245
	v_add_f32_e32 v246, v129, v246
	v_cvt_pk_bf16_f32 v166, v124, v125
	v_cvt_pk_bf16_f32 v167, v126, v127
	ds_read_b64_tr_b16 v[124:125], v243 offset:26624
	ds_read_b64_tr_b16 v[126:127], v243 offset:27136
	v_mfma_f32_32x32x16_bf16 v[96:111], v[180:183], v[144:147], v[64:79]
	v_add_f32_e32 v245, v130, v245
	v_add_f32_e32 v246, v131, v246
	v_add_f32_e32 v245, v132, v245
	v_add_f32_e32 v246, v133, v246
	v_cvt_pk_bf16_f32 v168, v128, v129
	v_cvt_pk_bf16_f32 v169, v130, v131
	ds_read_b64_tr_b16 v[128:129], v243 offset:30720
	ds_read_b64_tr_b16 v[130:131], v243 offset:31232
	v_mfma_f32_32x32x16_bf16 v[96:111], v[188:191], v[148:151], v[96:111]
	v_add_f32_e32 v245, v134, v245
	v_add_f32_e32 v246, v135, v246
	v_add_f32_e32 v245, v136, v245
	v_add_f32_e32 v246, v137, v246
	v_cvt_pk_bf16_f32 v170, v132, v133
	v_cvt_pk_bf16_f32 v171, v134, v135
	ds_read_b64_tr_b16 v[132:133], v243 offset:27648
	ds_read_b64_tr_b16 v[134:135], v243 offset:28160
	v_mfma_f32_32x32x16_bf16 v[96:111], v[196:199], v[152:155], v[96:111]
	v_add_f32_e32 v245, v138, v245
	v_add_f32_e32 v246, v139, v246
	v_add_f32_e32 v245, v140, v245
	v_add_f32_e32 v246, v141, v246
	v_cvt_pk_bf16_f32 v172, v136, v137
	v_cvt_pk_bf16_f32 v173, v138, v139
	ds_read_b64_tr_b16 v[136:137], v243 offset:31744
	ds_read_b64_tr_b16 v[138:139], v243 offset:32256
	v_mfma_f32_32x32x16_bf16 v[96:111], v[206:209], v[156:159], v[96:111]
	v_add_f32_e32 v245, v142, v245
	v_add_f32_e32 v246, v143, v246
	v_add_f32_e32 v245, v245, v246
	v_cvt_pk_bf16_f32 v174, v140, v141
	v_cvt_pk_bf16_f32 v175, v142, v143
	v_add_f32_e32 v211, v211, v245
	v_add_u32_e32 v244, s18, v219
	s_waitcnt lgkmcnt(8)
	v_mfma_f32_32x32x16_bf16 v[0:15], v[160:163], v[214:217], v[0:15]
	v_max3_f32 v246, v80, v81, v82
	v_max3_f32 v247, v83, v84, v85
	ds_read_b64_tr_b16 v[214:215], v243 offset:49152
	ds_read_b64_tr_b16 v[216:217], v243 offset:49664
	v_mfma_f32_32x32x16_bf16 v[16:31], v[160:163], v[112:115], v[16:31]
	s_add_i32 m0, s17, s54
	v_max3_f32 v246, v246, v86, v87
	v_max3_f32 v247, v247, v88, v89
	v_max3_f32 v246, v246, v90, v91
	v_max3_f32 v247, v247, v92, v93
	ds_read_b64_tr_b16 v[112:113], v243 offset:53248
	ds_read_b64_tr_b16 v[114:115], v243 offset:53760
	global_load_lds_dwordx4 v222, s[0:1]
	s_add_u32 s0, s0, 0x20000
	s_addc_u32 s1, s1, 0
	v_mfma_f32_32x32x16_bf16 v[0:15], v[164:167], v[116:119], v[0:15]
	s_add_i32 s21, s18, s54
	s_add_i32 m0, s21, 0x6000
	v_max3_f32 v246, v246, v94, v95
	v_max3_f32 v247, v247, v96, v97
	v_max3_f32 v246, v246, v98, v99
	v_max3_f32 v247, v247, v100, v101
	ds_read_b64_tr_b16 v[116:117], v243 offset:50176
	ds_read_b64_tr_b16 v[118:119], v243 offset:50688
	global_load_lds_dwordx4 v223, s[4:5]
	v_mfma_f32_32x32x16_bf16 v[16:31], v[164:167], v[120:123], v[16:31]
	s_add_i32 m0, s21, 0xc000
	v_max3_f32 v246, v246, v102, v103
	v_max3_f32 v247, v247, v104, v105
	v_max3_f32 v246, v246, v106, v107
	v_max3_f32 v247, v247, v108, v109
	ds_read_b64_tr_b16 v[120:121], v243 offset:54272
	ds_read_b64_tr_b16 v[122:123], v243 offset:54784
	global_load_lds_dwordx4 v224, s[4:5]
	s_add_u32 s4, s4, 0x20000
	s_addc_u32 s5, s5, 0
	s_waitcnt lgkmcnt(8)
	v_mfma_f32_32x32x16_bf16 v[0:15], v[168:171], v[124:127], v[0:15]
	v_max3_f32 v246, v246, v110, v111
	v_max_f32_e32 v248, v246, v247
	ds_read_b64_tr_b16 v[124:125], v243 offset:51200
	ds_read_b64_tr_b16 v[126:127], v243 offset:51712
	v_cmp_lt_f32_e32 vcc, s87, v248
	s_cbranch_vccnz .Lat_rare_M2

.Lat_step_T5:
	v_add_u32_e32 v243, s16, v204
	ds_read_b64_tr_b16 v[214:215], v243 offset:24576
	ds_read_b64_tr_b16 v[216:217], v243 offset:25088
	v_mfma_f32_32x32x16_bf16 v[112:127], v[176:179], v[144:147], v[64:79]
	v_add_f32_e32 v245, v80, v81
	v_add_f32_e32 v246, v82, v83
	v_add_f32_e32 v245, v84, v245
	v_add_f32_e32 v246, v85, v246
	v_cvt_pk_bf16_f32 v160, v80, v81
	v_cvt_pk_bf16_f32 v161, v82, v83
	ds_read_b64_tr_b16 v[80:81], v243 offset:28672
	ds_read_b64_tr_b16 v[82:83], v243 offset:29184
	v_mfma_f32_32x32x16_bf16 v[112:127], v[184:187], v[148:151], v[112:127]
	v_add_f32_e32 v245, v86, v245
	v_add_f32_e32 v246, v87, v246
	v_add_f32_e32 v245, v88, v245
	v_add_f32_e32 v246, v89, v246
	v_cvt_pk_bf16_f32 v162, v84, v85
	v_cvt_pk_bf16_f32 v163, v86, v87
	ds_read_b64_tr_b16 v[84:85], v243 offset:25600
	ds_read_b64_tr_b16 v[86:87], v243 offset:26112
	v_mfma_f32_32x32x16_bf16 v[112:127], v[192:195], v[152:155], v[112:127]
	v_add_f32_e32 v245, v90, v245
	v_add_f32_e32 v246, v91, v246
	v_add_f32_e32 v245, v92, v245
	v_add_f32_e32 v246, v93, v246
	v_cvt_pk_bf16_f32 v164, v88, v89
	v_cvt_pk_bf16_f32 v165, v90, v91
	ds_read_b64_tr_b16 v[88:89], v243 offset:29696
	ds_read_b64_tr_b16 v[90:91], v243 offset:30208
	v_mfma_f32_32x32x16_bf16 v[112:127], v[200:203], v[156:159], v[112:127]
	v_add_f32_e32 v245, v94, v245
	v_add_f32_e32 v246, v95, v246
	v_add_f32_e32 v245, v96, v245
	v_add_f32_e32 v246, v97, v246
	v_cvt_pk_bf16_f32 v166, v92, v93
	v_cvt_pk_bf16_f32 v167, v94, v95
	ds_read_b64_tr_b16 v[92:93], v243 offset:26624
	ds_read_b64_tr_b16 v[94:95], v243 offset:27136
	v_mfma_f32_32x32x16_bf16 v[128:143], v[180:183], v[144:147], v[64:79]
	v_add_f32_e32 v245, v98, v245
	v_add_f32_e32 v246, v99, v246
	v_add_f32_e32 v245, v100, v245
	v_add_f32_e32 v246, v101, v246
	v_cvt_pk_bf16_f32 v168, v96, v97
	v_cvt_pk_bf16_f32 v169, v98, v99
	ds_read_b64_tr_b16 v[96:97], v243 offset:30720
	ds_read_b64_tr_b16 v[98:99], v243 offset:31232
	v_mfma_f32_32x32x16_bf16 v[128:143], v[188:191], v[148:151], v[128:143]
	v_add_f32_e32 v245, v102, v245
	v_add_f32_e32 v246, v103, v246
	v_add_f32_e32 v245, v104, v245
	v_add_f32_e32 v246, v105, v246
	v_cvt_pk_bf16_f32 v170, v100, v101
	v_cvt_pk_bf16_f32 v171, v102, v103
	ds_read_b64_tr_b16 v[100:101], v243 offset:27648
	ds_read_b64_tr_b16 v[102:103], v243 offset:28160
	v_mfma_f32_32x32x16_bf16 v[128:143], v[196:199], v[152:155], v[128:143]
	v_add_f32_e32 v245, v106, v245
	v_add_f32_e32 v246, v107, v246
	v_add_f32_e32 v245, v108, v245
	v_add_f32_e32 v246, v109, v246
	v_cvt_pk_bf16_f32 v172, v104, v105
	v_cvt_pk_bf16_f32 v173, v106, v107
	ds_read_b64_tr_b16 v[104:105], v243 offset:31744
	ds_read_b64_tr_b16 v[106:107], v243 offset:32256
	v_mfma_f32_32x32x16_bf16 v[128:143], v[206:209], v[156:159], v[128:143]
	v_add_f32_e32 v245, v110, v245
	v_add_f32_e32 v246, v111, v246
	v_add_f32_e32 v245, v245, v246
	v_cvt_pk_bf16_f32 v174, v108, v109
	v_cvt_pk_bf16_f32 v175, v110, v111
	v_add_f32_e32 v211, v211, v245
	v_add_u32_e32 v244, s18, v219
	s_waitcnt lgkmcnt(8)
	v_mfma_f32_32x32x16_bf16 v[0:15], v[160:163], v[214:217], v[0:15]
	v_max3_f32 v246, v112, v113, v114
	v_max3_f32 v247, v115, v116, v117
	ds_read_b64_tr_b16 v[214:215], v243 offset:49152
	ds_read_b64_tr_b16 v[216:217], v243 offset:49664
	v_mfma_f32_32x32x16_bf16 v[16:31], v[160:163], v[80:83], v[16:31]
	s_add_i32 m0, s17, s54
	v_max3_f32 v246, v246, v118, v119
	v_max3_f32 v247, v247, v120, v121
	v_max3_f32 v246, v246, v122, v123
	v_max3_f32 v247, v247, v124, v125
	ds_read_b64_tr_b16 v[80:81], v243 offset:53248
	ds_read_b64_tr_b16 v[82:83], v243 offset:53760
	global_load_lds_dwordx4 v222, s[0:1]
	s_add_u32 s0, s0, 0x20000
	s_addc_u32 s1, s1, 0
	v_mfma_f32_32x32x16_bf16 v[0:15], v[164:167], v[84:87], v[0:15]
	s_add_i32 s21, s18, s54
	s_add_i32 m0, s21, 0x6000
	v_max3_f32 v246, v246, v126, v127
	v_max3_f32 v247, v247, v128, v129
	v_max3_f32 v246, v246, v130, v131
	v_max3_f32 v247, v247, v132, v133
	ds_read_b64_tr_b16 v[84:85], v243 offset:50176
	ds_read_b64_tr_b16 v[86:87], v243 offset:50688
	global_load_lds_dwordx4 v223, s[4:5]
	v_mfma_f32_32x32x16_bf16 v[16:31], v[164:167], v[88:91], v[16:31]
	s_add_i32 m0, s21, 0xc000
	v_max3_f32 v246, v246, v134, v135
	v_max3_f32 v247, v247, v136, v137
	v_max3_f32 v246, v246, v138, v139
	v_max3_f32 v247, v247, v140, v141
	ds_read_b64_tr_b16 v[88:89], v243 offset:54272
	ds_read_b64_tr_b16 v[90:91], v243 offset:54784
	global_load_lds_dwordx4 v224, s[4:5]
	s_add_u32 s4, s4, 0x20000
	s_addc_u32 s5, s5, 0
	s_waitcnt lgkmcnt(8)
	v_mfma_f32_32x32x16_bf16 v[0:15], v[168:171], v[92:95], v[0:15]
	v_max3_f32 v246, v246, v142, v143
	v_max_f32_e32 v248, v246, v247
	ds_read_b64_tr_b16 v[92:93], v243 offset:51200
	ds_read_b64_tr_b16 v[94:95], v243 offset:51712
	v_cmp_lt_f32_e32 vcc, s87, v248
	s_cbranch_vccnz .Lat_rare_T5

.Lat_step_T4:
	v_add_u32_e32 v243, s16, v204
	ds_read_b64_tr_b16 v[214:215], v243 offset:24576
	ds_read_b64_tr_b16 v[216:217], v243 offset:25088
	v_mfma_f32_32x32x16_bf16 v[80:95], v[176:179], v[144:147], v[64:79]
	v_add_f32_e32 v245, v112, v113
	v_add_f32_e32 v246, v114, v115
	v_add_f32_e32 v245, v116, v245
	v_add_f32_e32 v246, v117, v246
	v_cvt_pk_bf16_f32 v160, v112, v113
	v_cvt_pk_bf16_f32 v161, v114, v115
	ds_read_b64_tr_b16 v[112:113], v243 offset:28672
	ds_read_b64_tr_b16 v[114:115], v243 offset:29184
	v_mfma_f32_32x32x16_bf16 v[80:95], v[184:187], v[148:151], v[80:95]
	v_add_f32_e32 v245, v118, v245
	v_add_f32_e32 v246, v119, v246
	v_add_f32_e32 v245, v120, v245
	v_add_f32_e32 v246, v121, v246
	v_cvt_pk_bf16_f32 v162, v116, v117
	v_cvt_pk_bf16_f32 v163, v118, v119
	ds_read_b64_tr_b16 v[116:117], v243 offset:25600
	ds_read_b64_tr_b16 v[118:119], v243 offset:26112
	v_mfma_f32_32x32x16_bf16 v[80:95], v[192:195], v[152:155], v[80:95]
	v_add_f32_e32 v245, v122, v245
	v_add_f32_e32 v246, v123, v246
	v_add_f32_e32 v245, v124, v245
	v_add_f32_e32 v246, v125, v246
	v_cvt_pk_bf16_f32 v164, v120, v121
	v_cvt_pk_bf16_f32 v165, v122, v123
	ds_read_b64_tr_b16 v[120:121], v243 offset:29696
	ds_read_b64_tr_b16 v[122:123], v243 offset:30208
	v_mfma_f32_32x32x16_bf16 v[80:95], v[200:203], v[156:159], v[80:95]
	v_add_f32_e32 v245, v126, v245
	v_add_f32_e32 v246, v127, v246
	v_add_f32_e32 v245, v128, v245
	v_add_f32_e32 v246, v129, v246
	v_cvt_pk_bf16_f32 v166, v124, v125
	v_cvt_pk_bf16_f32 v167, v126, v127
	ds_read_b64_tr_b16 v[124:125], v243 offset:26624
	ds_read_b64_tr_b16 v[126:127], v243 offset:27136
	v_mfma_f32_32x32x16_bf16 v[96:111], v[180:183], v[144:147], v[64:79]
	v_add_f32_e32 v245, v130, v245
	v_add_f32_e32 v246, v131, v246
	v_add_f32_e32 v245, v132, v245
	v_add_f32_e32 v246, v133, v246
	v_cvt_pk_bf16_f32 v168, v128, v129
	v_cvt_pk_bf16_f32 v169, v130, v131
	ds_read_b64_tr_b16 v[128:129], v243 offset:30720
	ds_read_b64_tr_b16 v[130:131], v243 offset:31232
	v_mfma_f32_32x32x16_bf16 v[96:111], v[188:191], v[148:151], v[96:111]
	v_add_f32_e32 v245, v134, v245
	v_add_f32_e32 v246, v135, v246
	v_add_f32_e32 v245, v136, v245
	v_add_f32_e32 v246, v137, v246
	v_cvt_pk_bf16_f32 v170, v132, v133
	v_cvt_pk_bf16_f32 v171, v134, v135
	ds_read_b64_tr_b16 v[132:133], v243 offset:27648
	ds_read_b64_tr_b16 v[134:135], v243 offset:28160
	v_mfma_f32_32x32x16_bf16 v[96:111], v[196:199], v[152:155], v[96:111]
	v_add_f32_e32 v245, v138, v245
	v_add_f32_e32 v246, v139, v246
	v_add_f32_e32 v245, v140, v245
	v_add_f32_e32 v246, v141, v246
	v_cvt_pk_bf16_f32 v172, v136, v137
	v_cvt_pk_bf16_f32 v173, v138, v139
	ds_read_b64_tr_b16 v[136:137], v243 offset:31744
	ds_read_b64_tr_b16 v[138:139], v243 offset:32256
	v_mfma_f32_32x32x16_bf16 v[96:111], v[206:209], v[156:159], v[96:111]
	v_add_f32_e32 v245, v142, v245
	v_add_f32_e32 v246, v143, v246
	v_add_f32_e32 v245, v245, v246
	v_cvt_pk_bf16_f32 v174, v140, v141
	v_cvt_pk_bf16_f32 v175, v142, v143
	v_add_f32_e32 v211, v211, v245
	v_add_u32_e32 v244, s18, v219
	s_waitcnt lgkmcnt(8)
; __device__ __forceinline__ void cmask(f32x16&p0,f32x16&p1,int jb,int qrel,int hi){
;   const float NEG=-INFINITY; int kb=64*jb+4*hi;
;   #pragma unroll
;   for(int r=0;r<16;++r){int kv=kb+(r&3)+8*(r>>2); if(kv>qrel)p0[r]=NEG; if(kv+32>qrel)p1[r]=NEG;}
; }
	v_mfma_f32_32x32x16_bf16 v[0:15], v[160:163], v[214:217], v[0:15]
	v_cmp_gt_i32_e64 s[28:29], 0, v225
	v_cmp_gt_i32_e64 s[30:31], 1, v225
	v_cmp_gt_i32_e64 s[34:35], 2, v225
	v_cndmask_b32_e64 v80, v80, v241, s[28:29]
	v_cmp_gt_i32_e64 s[28:29], 3, v225
	v_cndmask_b32_e64 v81, v81, v241, s[30:31]
	v_cmp_gt_i32_e64 s[30:31], 8, v225
	v_cndmask_b32_e64 v82, v82, v241, s[34:35]
	v_cmp_gt_i32_e64 s[34:35], 9, v225
	v_cndmask_b32_e64 v83, v83, v241, s[28:29]
	ds_read_b64_tr_b16 v[214:215], v243 offset:49152
	ds_read_b64_tr_b16 v[216:217], v243 offset:49664
	v_mfma_f32_32x32x16_bf16 v[16:31], v[160:163], v[112:115], v[16:31]
	s_add_i32 m0, s17, s54
	v_cmp_gt_i32_e64 s[28:29], 10, v225
	v_cndmask_b32_e64 v84, v84, v241, s[30:31]
	v_cmp_gt_i32_e64 s[30:31], 11, v225
	v_cndmask_b32_e64 v85, v85, v241, s[34:35]
	v_cmp_gt_i32_e64 s[34:35], 16, v225
	v_cndmask_b32_e64 v86, v86, v241, s[28:29]
	v_cmp_gt_i32_e64 s[28:29], 17, v225
	v_cndmask_b32_e64 v87, v87, v241, s[30:31]
	v_cmp_gt_i32_e64 s[30:31], 18, v225
	v_cndmask_b32_e64 v88, v88, v241, s[34:35]
	ds_read_b64_tr_b16 v[112:113], v243 offset:53248
	ds_read_b64_tr_b16 v[114:115], v243 offset:53760
	global_load_lds_dwordx4 v222, s[0:1]
	s_add_u32 s0, s0, 0x20000
	s_addc_u32 s1, s1, 0
	v_mfma_f32_32x32x16_bf16 v[0:15], v[164:167], v[116:119], v[0:15]
	s_add_i32 s21, s18, s54
	s_add_i32 m0, s21, 0x6000
	v_cmp_gt_i32_e64 s[34:35], 19, v225
	v_cndmask_b32_e64 v89, v89, v241, s[28:29]
	v_cmp_gt_i32_e64 s[28:29], 24, v225
	v_cndmask_b32_e64 v90, v90, v241, s[30:31]
	v_cmp_gt_i32_e64 s[30:31], 25, v225
	v_cndmask_b32_e64 v91, v91, v241, s[34:35]
	v_cmp_gt_i32_e64 s[34:35], 26, v225
	v_cndmask_b32_e64 v92, v92, v241, s[28:29]
	v_cmp_gt_i32_e64 s[28:29], 27, v225
	v_cndmask_b32_e64 v93, v93, v241, s[30:31]
	ds_read_b64_tr_b16 v[116:117], v243 offset:50176
	ds_read_b64_tr_b16 v[118:119], v243 offset:50688
	global_load_lds_dwordx4 v223, s[4:5]
	v_mfma_f32_32x32x16_bf16 v[16:31], v[164:167], v[120:123], v[16:31]
	s_add_i32 m0, s21, 0xc000
	v_cmp_gt_i32_e64 s[30:31], 32, v225
	v_cndmask_b32_e64 v94, v94, v241, s[34:35]
	v_cmp_gt_i32_e64 s[34:35], 33, v225
	v_cndmask_b32_e64 v95, v95, v241, s[28:29]
	v_cmp_gt_i32_e64 s[28:29], 34, v225
	v_cndmask_b32_e64 v96, v96, v241, s[30:31]
	v_cmp_gt_i32_e64 s[30:31], 35, v225
	v_cndmask_b32_e64 v97, v97, v241, s[34:35]
	v_cmp_gt_i32_e64 s[34:35], 40, v225
	v_cndmask_b32_e64 v98, v98, v241, s[28:29]
	ds_read_b64_tr_b16 v[120:121], v243 offset:54272
	ds_read_b64_tr_b16 v[122:123], v243 offset:54784
	global_load_lds_dwordx4 v224, s[4:5]
	s_add_u32 s4, s4, 0x20000
	s_addc_u32 s5, s5, 0
	s_waitcnt lgkmcnt(8)
	v_mfma_f32_32x32x16_bf16 v[0:15], v[168:171], v[124:127], v[0:15]
	v_cmp_gt_i32_e64 s[28:29], 41, v225
	v_cndmask_b32_e64 v99, v99, v241, s[30:31]
	v_cmp_gt_i32_e64 s[30:31], 42, v225
	v_cndmask_b32_e64 v100, v100, v241, s[34:35]
	v_cmp_gt_i32_e64 s[34:35], 43, v225
	v_cndmask_b32_e64 v101, v101, v241, s[28:29]
	v_cmp_gt_i32_e64 s[28:29], 48, v225
	v_cndmask_b32_e64 v102, v102, v241, s[30:31]
	v_cmp_gt_i32_e64 s[30:31], 49, v225
	v_cndmask_b32_e64 v103, v103, v241, s[34:35]
	ds_read_b64_tr_b16 v[124:125], v243 offset:51200
	ds_read_b64_tr_b16 v[126:127], v243 offset:51712
	v_mfma_f32_32x32x16_bf16 v[16:31], v[168:171], v[128:131], v[16:31]
	v_cmp_gt_i32_e64 s[34:35], 50, v225
	v_cndmask_b32_e64 v104, v104, v241, s[28:29]
	v_cmp_gt_i32_e64 s[28:29], 51, v225
	v_cndmask_b32_e64 v105, v105, v241, s[30:31]
	v_cmp_gt_i32_e64 s[30:31], 56, v225
	v_cndmask_b32_e64 v106, v106, v241, s[34:35]
	v_cmp_gt_i32_e64 s[34:35], 57, v225
	v_cndmask_b32_e64 v107, v107, v241, s[28:29]
	v_cmp_gt_i32_e64 s[28:29], 58, v225
	v_cndmask_b32_e64 v108, v108, v241, s[30:31]
	ds_read_b64_tr_b16 v[128:129], v243 offset:55296
	ds_read_b64_tr_b16 v[130:131], v243 offset:55808
	v_mfma_f32_32x32x16_bf16 v[0:15], v[172:175], v[132:135], v[0:15]
	v_cmp_gt_i32_e64 s[30:31], 59, v225
	v_cndmask_b32_e64 v109, v109, v241, s[34:35]
	v_cndmask_b32_e64 v110, v110, v241, s[28:29]
	v_cndmask_b32_e64 v111, v111, v241, s[30:31]
	v_max3_f32 v246, v80, v81, v82
	v_max3_f32 v247, v83, v84, v85
	v_max3_f32 v246, v246, v86, v87
	v_max3_f32 v247, v247, v88, v89
	v_max3_f32 v246, v246, v90, v91
	v_max3_f32 v247, v247, v92, v93
	ds_read_b64_tr_b16 v[132:133], v243 offset:52224
	ds_read_b64_tr_b16 v[134:135], v243 offset:52736
	v_mfma_f32_32x32x16_bf16 v[16:31], v[172:175], v[136:139], v[16:31]
	v_max3_f32 v246, v246, v94, v95
	v_max3_f32 v247, v247, v96, v97
	v_max3_f32 v246, v246, v98, v99
	v_max3_f32 v247, v247, v100, v101
	v_max3_f32 v246, v246, v102, v103
	v_max3_f32 v247, v247, v104, v105
	v_max3_f32 v246, v246, v106, v107
	v_max3_f32 v247, v247, v108, v109
	v_max3_f32 v246, v246, v110, v111
	v_max_f32_e32 v248, v246, v247
	ds_read_b64_tr_b16 v[136:137], v243 offset:56320
	ds_read_b64_tr_b16 v[138:139], v243 offset:56832
	s_waitcnt lgkmcnt(8)
	v_mfma_f32_32x32x16_bf16 v[32:47], v[160:163], v[214:217], v[32:47]
	ds_read_b128 v[176:179], v244 offset:0
	ds_read_b128 v[180:183], v244 offset:512
	v_cmp_lt_f32_e32 vcc, s87, v248
	s_cbranch_vccnz .Lat_rare_T4

.Lat_step_T3:
	s_cmp_lt_u32 s55, 1
	s_cbranch_scc1 .Lat_T3_light
	v_add_u32_e32 v243, s16, v204
	ds_read_b64_tr_b16 v[214:215], v243 offset:24576
	ds_read_b64_tr_b16 v[216:217], v243 offset:25088
	v_mfma_f32_32x32x16_bf16 v[112:127], v[176:179], v[144:147], v[64:79]
	v_add_f32_e32 v245, v80, v81
	v_add_f32_e32 v246, v82, v83
	v_add_f32_e32 v245, v84, v245
	v_add_f32_e32 v246, v85, v246
	v_cvt_pk_bf16_f32 v160, v80, v81
	v_cvt_pk_bf16_f32 v161, v82, v83
	ds_read_b64_tr_b16 v[80:81], v243 offset:28672
	ds_read_b64_tr_b16 v[82:83], v243 offset:29184
	v_mfma_f32_32x32x16_bf16 v[112:127], v[184:187], v[148:151], v[112:127]
	v_add_f32_e32 v245, v86, v245
	v_add_f32_e32 v246, v87, v246
	v_add_f32_e32 v245, v88, v245
	v_add_f32_e32 v246, v89, v246
	v_cvt_pk_bf16_f32 v162, v84, v85
	v_cvt_pk_bf16_f32 v163, v86, v87
	ds_read_b64_tr_b16 v[84:85], v243 offset:25600
	ds_read_b64_tr_b16 v[86:87], v243 offset:26112
	v_mfma_f32_32x32x16_bf16 v[112:127], v[192:195], v[152:155], v[112:127]
	v_add_f32_e32 v245, v90, v245
	v_add_f32_e32 v246, v91, v246
	v_add_f32_e32 v245, v92, v245
	v_add_f32_e32 v246, v93, v246
	v_cvt_pk_bf16_f32 v164, v88, v89
	v_cvt_pk_bf16_f32 v165, v90, v91
	ds_read_b64_tr_b16 v[88:89], v243 offset:29696
	ds_read_b64_tr_b16 v[90:91], v243 offset:30208
	v_mfma_f32_32x32x16_bf16 v[112:127], v[200:203], v[156:159], v[112:127]
	v_add_f32_e32 v245, v94, v245
	v_add_f32_e32 v246, v95, v246
	v_add_f32_e32 v245, v96, v245
	v_add_f32_e32 v246, v97, v246
	v_cvt_pk_bf16_f32 v166, v92, v93
	v_cvt_pk_bf16_f32 v167, v94, v95
	ds_read_b64_tr_b16 v[92:93], v243 offset:26624
	ds_read_b64_tr_b16 v[94:95], v243 offset:27136
	v_mfma_f32_32x32x16_bf16 v[128:143], v[180:183], v[144:147], v[64:79]
	v_add_f32_e32 v245, v98, v245
	v_add_f32_e32 v246, v99, v246
	v_add_f32_e32 v245, v100, v245
	v_add_f32_e32 v246, v101, v246
	v_cvt_pk_bf16_f32 v168, v96, v97
	v_cvt_pk_bf16_f32 v169, v98, v99
	ds_read_b64_tr_b16 v[96:97], v243 offset:30720
	ds_read_b64_tr_b16 v[98:99], v243 offset:31232
	v_mfma_f32_32x32x16_bf16 v[128:143], v[188:191], v[148:151], v[128:143]
	v_add_f32_e32 v245, v102, v245
	v_add_f32_e32 v246, v103, v246
	v_add_f32_e32 v245, v104, v245
	v_add_f32_e32 v246, v105, v246
	v_cvt_pk_bf16_f32 v170, v100, v101
	v_cvt_pk_bf16_f32 v171, v102, v103
	ds_read_b64_tr_b16 v[100:101], v243 offset:27648
	ds_read_b64_tr_b16 v[102:103], v243 offset:28160
	v_mfma_f32_32x32x16_bf16 v[128:143], v[196:199], v[152:155], v[128:143]
	v_add_f32_e32 v245, v106, v245
	v_add_f32_e32 v246, v107, v246
	v_add_f32_e32 v245, v108, v245
	v_add_f32_e32 v246, v109, v246
	v_cvt_pk_bf16_f32 v172, v104, v105
	v_cvt_pk_bf16_f32 v173, v106, v107
	ds_read_b64_tr_b16 v[104:105], v243 offset:31744
	ds_read_b64_tr_b16 v[106:107], v243 offset:32256
	v_mfma_f32_32x32x16_bf16 v[128:143], v[206:209], v[156:159], v[128:143]
	v_add_f32_e32 v245, v110, v245
	v_add_f32_e32 v246, v111, v246
	v_add_f32_e32 v245, v245, v246
	v_cvt_pk_bf16_f32 v174, v108, v109
	v_cvt_pk_bf16_f32 v175, v110, v111
	v_add_f32_e32 v211, v211, v245
	v_add_u32_e32 v244, s18, v219
	s_waitcnt lgkmcnt(8)
; __device__ __forceinline__ void cmask(f32x16&p0,f32x16&p1,int jb,int qrel,int hi){
;   const float NEG=-INFINITY; int kb=64*jb+4*hi;
;   #pragma unroll
;   for(int r=0;r<16;++r){int kv=kb+(r&3)+8*(r>>2); if(kv>qrel)p0[r]=NEG; if(kv+32>qrel)p1[r]=NEG;}
; }
	v_mfma_f32_32x32x16_bf16 v[0:15], v[160:163], v[214:217], v[0:15]
	v_add_u32_e32 v242, 0xffffffc0, v225
	v_cmp_gt_i32_e64 s[28:29], 0, v242
	v_cmp_gt_i32_e64 s[30:31], 1, v242
	v_cmp_gt_i32_e64 s[34:35], 2, v242
	v_cndmask_b32_e64 v112, v112, v241, s[28:29]
	v_cmp_gt_i32_e64 s[28:29], 3, v242
	v_cndmask_b32_e64 v113, v113, v241, s[30:31]
	v_cmp_gt_i32_e64 s[30:31], 8, v242
	v_cndmask_b32_e64 v114, v114, v241, s[34:35]
	v_cmp_gt_i32_e64 s[34:35], 9, v242
	ds_read_b64_tr_b16 v[214:215], v243 offset:49152
	ds_read_b64_tr_b16 v[216:217], v243 offset:49664
	v_mfma_f32_32x32x16_bf16 v[16:31], v[160:163], v[80:83], v[16:31]
	v_cndmask_b32_e64 v115, v115, v241, s[28:29]
	v_cmp_gt_i32_e64 s[28:29], 10, v242
	v_cndmask_b32_e64 v116, v116, v241, s[30:31]
	v_cmp_gt_i32_e64 s[30:31], 11, v242
	v_cndmask_b32_e64 v117, v117, v241, s[34:35]
	v_cmp_gt_i32_e64 s[34:35], 16, v242
	v_cndmask_b32_e64 v118, v118, v241, s[28:29]
	v_cmp_gt_i32_e64 s[28:29], 17, v242
	v_cndmask_b32_e64 v119, v119, v241, s[30:31]
	v_cmp_gt_i32_e64 s[30:31], 18, v242
	ds_read_b64_tr_b16 v[80:81], v243 offset:53248
	ds_read_b64_tr_b16 v[82:83], v243 offset:53760
	v_mfma_f32_32x32x16_bf16 v[0:15], v[164:167], v[84:87], v[0:15]
	s_add_i32 s21, s18, s54
	s_add_i32 m0, s21, 0x6000
	v_cndmask_b32_e64 v120, v120, v241, s[34:35]
	v_cmp_gt_i32_e64 s[34:35], 19, v242
	v_cndmask_b32_e64 v121, v121, v241, s[28:29]
	v_cmp_gt_i32_e64 s[28:29], 24, v242
	v_cndmask_b32_e64 v122, v122, v241, s[30:31]
	v_cmp_gt_i32_e64 s[30:31], 25, v242
	v_cndmask_b32_e64 v123, v123, v241, s[34:35]
	v_cmp_gt_i32_e64 s[34:35], 26, v242
	v_cndmask_b32_e64 v124, v124, v241, s[28:29]
	v_cmp_gt_i32_e64 s[28:29], 27, v242
	ds_read_b64_tr_b16 v[84:85], v243 offset:50176
	ds_read_b64_tr_b16 v[86:87], v243 offset:50688
	global_load_lds_dwordx4 v223, s[4:5]
	v_mfma_f32_32x32x16_bf16 v[16:31], v[164:167], v[88:91], v[16:31]
	s_add_i32 m0, s21, 0xc000
	v_cndmask_b32_e64 v125, v125, v241, s[30:31]
	v_cmp_gt_i32_e64 s[30:31], 32, v242
	v_cndmask_b32_e64 v126, v126, v241, s[34:35]
	v_cmp_gt_i32_e64 s[34:35], 33, v242
	v_cndmask_b32_e64 v127, v127, v241, s[28:29]
	v_cmp_gt_i32_e64 s[28:29], 34, v242
	v_cndmask_b32_e64 v128, v128, v241, s[30:31]
	v_cmp_gt_i32_e64 s[30:31], 35, v242
	v_cndmask_b32_e64 v129, v129, v241, s[34:35]
	v_cmp_gt_i32_e64 s[34:35], 40, v242
	ds_read_b64_tr_b16 v[88:89], v243 offset:54272
	ds_read_b64_tr_b16 v[90:91], v243 offset:54784
	global_load_lds_dwordx4 v224, s[4:5]
	s_add_u32 s4, s4, 0x20000
	s_addc_u32 s5, s5, 0
	s_waitcnt lgkmcnt(8)
	v_mfma_f32_32x32x16_bf16 v[0:15], v[168:171], v[92:95], v[0:15]
	v_cndmask_b32_e64 v130, v130, v241, s[28:29]
	v_cmp_gt_i32_e64 s[28:29], 41, v242
	v_cndmask_b32_e64 v131, v131, v241, s[30:31]
	v_cmp_gt_i32_e64 s[30:31], 42, v242
	v_cndmask_b32_e64 v132, v132, v241, s[34:35]
	v_cmp_gt_i32_e64 s[34:35], 43, v242
	v_cndmask_b32_e64 v133, v133, v241, s[28:29]
	v_cmp_gt_i32_e64 s[28:29], 48, v242
	v_cndmask_b32_e64 v134, v134, v241, s[30:31]
	v_cmp_gt_i32_e64 s[30:31], 49, v242
	ds_read_b64_tr_b16 v[92:93], v243 offset:51200
	ds_read_b64_tr_b16 v[94:95], v243 offset:51712
	v_mfma_f32_32x32x16_bf16 v[16:31], v[168:171], v[96:99], v[16:31]
	v_cndmask_b32_e64 v135, v135, v241, s[34:35]
	v_cmp_gt_i32_e64 s[34:35], 50, v242
	v_cndmask_b32_e64 v136, v136, v241, s[28:29]
	v_cmp_gt_i32_e64 s[28:29], 51, v242
	v_cndmask_b32_e64 v137, v137, v241, s[30:31]
	v_cmp_gt_i32_e64 s[30:31], 56, v242
	v_cndmask_b32_e64 v138, v138, v241, s[34:35]
	v_cmp_gt_i32_e64 s[34:35], 57, v242
	v_cndmask_b32_e64 v139, v139, v241, s[28:29]
	v_cmp_gt_i32_e64 s[28:29], 58, v242
	ds_read_b64_tr_b16 v[96:97], v243 offset:55296
	ds_read_b64_tr_b16 v[98:99], v243 offset:55808
	v_mfma_f32_32x32x16_bf16 v[0:15], v[172:175], v[100:103], v[0:15]
	v_cndmask_b32_e64 v140, v140, v241, s[30:31]
	v_cmp_gt_i32_e64 s[30:31], 59, v242
	v_cndmask_b32_e64 v141, v141, v241, s[34:35]
	v_cndmask_b32_e64 v142, v142, v241, s[28:29]
	v_cndmask_b32_e64 v143, v143, v241, s[30:31]
	v_max3_f32 v246, v112, v113, v114
	v_max3_f32 v247, v115, v116, v117
	v_max3_f32 v246, v246, v118, v119
	v_max3_f32 v247, v247, v120, v121
	v_max3_f32 v246, v246, v122, v123
	ds_read_b64_tr_b16 v[100:101], v243 offset:52224
	ds_read_b64_tr_b16 v[102:103], v243 offset:52736
	v_mfma_f32_32x32x16_bf16 v[16:31], v[172:175], v[104:107], v[16:31]
	v_max3_f32 v247, v247, v124, v125
	v_max3_f32 v246, v246, v126, v127
	v_max3_f32 v247, v247, v128, v129
	v_max3_f32 v246, v246, v130, v131
	v_max3_f32 v247, v247, v132, v133
	v_max3_f32 v246, v246, v134, v135
	v_max3_f32 v247, v247, v136, v137
	v_max3_f32 v246, v246, v138, v139
	v_max3_f32 v247, v247, v140, v141
	v_max3_f32 v246, v246, v142, v143
	ds_read_b64_tr_b16 v[104:105], v243 offset:56320
	ds_read_b64_tr_b16 v[106:107], v243 offset:56832
	s_waitcnt lgkmcnt(8)
	v_mfma_f32_32x32x16_bf16 v[32:47], v[160:163], v[214:217], v[32:47]
	v_max_f32_e32 v248, v246, v247
	ds_read_b128 v[176:179], v244 offset:0
	ds_read_b128 v[180:183], v244 offset:512
	v_cmp_lt_f32_e32 vcc, s87, v248
	s_cbranch_vccnz .Lat_rare_T3

.Lat_T3_end:
.Lat_step_T2:
	s_cmp_lt_u32 s55, 2
	s_cbranch_scc1 .Lat_T2_light
	v_add_u32_e32 v243, s16, v204
	ds_read_b64_tr_b16 v[214:215], v243 offset:24576
	ds_read_b64_tr_b16 v[216:217], v243 offset:25088
	v_mfma_f32_32x32x16_bf16 v[80:95], v[176:179], v[144:147], v[64:79]
	v_add_f32_e32 v245, v112, v113
	v_add_f32_e32 v246, v114, v115
	v_add_f32_e32 v245, v116, v245
	v_add_f32_e32 v246, v117, v246
	v_cvt_pk_bf16_f32 v160, v112, v113
	v_cvt_pk_bf16_f32 v161, v114, v115
	ds_read_b64_tr_b16 v[112:113], v243 offset:28672
	ds_read_b64_tr_b16 v[114:115], v243 offset:29184
	v_mfma_f32_32x32x16_bf16 v[80:95], v[184:187], v[148:151], v[80:95]
	v_add_f32_e32 v245, v118, v245
	v_add_f32_e32 v246, v119, v246
	v_add_f32_e32 v245, v120, v245
	v_add_f32_e32 v246, v121, v246
	v_cvt_pk_bf16_f32 v162, v116, v117
	v_cvt_pk_bf16_f32 v163, v118, v119
	ds_read_b64_tr_b16 v[116:117], v243 offset:25600
	ds_read_b64_tr_b16 v[118:119], v243 offset:26112
	v_mfma_f32_32x32x16_bf16 v[80:95], v[192:195], v[152:155], v[80:95]
	v_add_f32_e32 v245, v122, v245
	v_add_f32_e32 v246, v123, v246
	v_add_f32_e32 v245, v124, v245
	v_add_f32_e32 v246, v125, v246
	v_cvt_pk_bf16_f32 v164, v120, v121
	v_cvt_pk_bf16_f32 v165, v122, v123
	ds_read_b64_tr_b16 v[120:121], v243 offset:29696
	ds_read_b64_tr_b16 v[122:123], v243 offset:30208
	v_mfma_f32_32x32x16_bf16 v[80:95], v[200:203], v[156:159], v[80:95]
	v_add_f32_e32 v245, v126, v245
	v_add_f32_e32 v246, v127, v246
	v_add_f32_e32 v245, v128, v245
	v_add_f32_e32 v246, v129, v246
	v_cvt_pk_bf16_f32 v166, v124, v125
	v_cvt_pk_bf16_f32 v167, v126, v127
	ds_read_b64_tr_b16 v[124:125], v243 offset:26624
	ds_read_b64_tr_b16 v[126:127], v243 offset:27136
	v_mfma_f32_32x32x16_bf16 v[96:111], v[180:183], v[144:147], v[64:79]
	v_add_f32_e32 v245, v130, v245
	v_add_f32_e32 v246, v131, v246
	v_add_f32_e32 v245, v132, v245
	v_add_f32_e32 v246, v133, v246
	v_cvt_pk_bf16_f32 v168, v128, v129
	v_cvt_pk_bf16_f32 v169, v130, v131
	ds_read_b64_tr_b16 v[128:129], v243 offset:30720
	ds_read_b64_tr_b16 v[130:131], v243 offset:31232
	v_mfma_f32_32x32x16_bf16 v[96:111], v[188:191], v[148:151], v[96:111]
	v_add_f32_e32 v245, v134, v245
	v_add_f32_e32 v246, v135, v246
	v_add_f32_e32 v245, v136, v245
	v_add_f32_e32 v246, v137, v246
	v_cvt_pk_bf16_f32 v170, v132, v133
	v_cvt_pk_bf16_f32 v171, v134, v135
	ds_read_b64_tr_b16 v[132:133], v243 offset:27648
	ds_read_b64_tr_b16 v[134:135], v243 offset:28160
	v_mfma_f32_32x32x16_bf16 v[96:111], v[196:199], v[152:155], v[96:111]
	v_add_f32_e32 v245, v138, v245
	v_add_f32_e32 v246, v139, v246
	v_add_f32_e32 v245, v140, v245
	v_add_f32_e32 v246, v141, v246
	v_cvt_pk_bf16_f32 v172, v136, v137
	v_cvt_pk_bf16_f32 v173, v138, v139
	ds_read_b64_tr_b16 v[136:137], v243 offset:31744
	ds_read_b64_tr_b16 v[138:139], v243 offset:32256
	v_mfma_f32_32x32x16_bf16 v[96:111], v[206:209], v[156:159], v[96:111]
	v_add_f32_e32 v245, v142, v245
	v_add_f32_e32 v246, v143, v246
	v_add_f32_e32 v245, v245, v246
	v_cvt_pk_bf16_f32 v174, v140, v141
	v_cvt_pk_bf16_f32 v175, v142, v143
	v_add_f32_e32 v211, v211, v245
	v_add_u32_e32 v244, s18, v219
	s_waitcnt lgkmcnt(8)
; __device__ __forceinline__ void cmask(f32x16&p0,f32x16&p1,int jb,int qrel,int hi){
;   const float NEG=-INFINITY; int kb=64*jb+4*hi;
;   #pragma unroll
;   for(int r=0;r<16;++r){int kv=kb+(r&3)+8*(r>>2); if(kv>qrel)p0[r]=NEG; if(kv+32>qrel)p1[r]=NEG;}
; }
	v_mfma_f32_32x32x16_bf16 v[0:15], v[160:163], v[214:217], v[0:15]
	v_add_u32_e32 v242, 0xffffff80, v225
	v_cmp_gt_i32_e64 s[28:29], 0, v242
	v_cmp_gt_i32_e64 s[30:31], 1, v242
	v_cmp_gt_i32_e64 s[34:35], 2, v242
	v_cndmask_b32_e64 v80, v80, v241, s[28:29]
	v_cmp_gt_i32_e64 s[28:29], 3, v242
	v_cndmask_b32_e64 v81, v81, v241, s[30:31]
	v_cmp_gt_i32_e64 s[30:31], 8, v242
	v_cndmask_b32_e64 v82, v82, v241, s[34:35]
	v_cmp_gt_i32_e64 s[34:35], 9, v242
	ds_read_b64_tr_b16 v[214:215], v243 offset:49152
	ds_read_b64_tr_b16 v[216:217], v243 offset:49664
	v_mfma_f32_32x32x16_bf16 v[16:31], v[160:163], v[112:115], v[16:31]
	v_cndmask_b32_e64 v83, v83, v241, s[28:29]
	v_cmp_gt_i32_e64 s[28:29], 10, v242
	v_cndmask_b32_e64 v84, v84, v241, s[30:31]
	v_cmp_gt_i32_e64 s[30:31], 11, v242
	v_cndmask_b32_e64 v85, v85, v241, s[34:35]
	v_cmp_gt_i32_e64 s[34:35], 16, v242
	v_cndmask_b32_e64 v86, v86, v241, s[28:29]
	v_cmp_gt_i32_e64 s[28:29], 17, v242
	v_cndmask_b32_e64 v87, v87, v241, s[30:31]
	v_cmp_gt_i32_e64 s[30:31], 18, v242
	ds_read_b64_tr_b16 v[112:113], v243 offset:53248
	ds_read_b64_tr_b16 v[114:115], v243 offset:53760
	v_mfma_f32_32x32x16_bf16 v[0:15], v[164:167], v[116:119], v[0:15]
	s_add_i32 s21, s18, s54
	s_add_i32 m0, s21, 0x6000
	v_cndmask_b32_e64 v88, v88, v241, s[34:35]
	v_cmp_gt_i32_e64 s[34:35], 19, v242
	v_cndmask_b32_e64 v89, v89, v241, s[28:29]
	v_cmp_gt_i32_e64 s[28:29], 24, v242
	v_cndmask_b32_e64 v90, v90, v241, s[30:31]
	v_cmp_gt_i32_e64 s[30:31], 25, v242
	v_cndmask_b32_e64 v91, v91, v241, s[34:35]
	v_cmp_gt_i32_e64 s[34:35], 26, v242
	v_cndmask_b32_e64 v92, v92, v241, s[28:29]
	v_cmp_gt_i32_e64 s[28:29], 27, v242
	ds_read_b64_tr_b16 v[116:117], v243 offset:50176
	ds_read_b64_tr_b16 v[118:119], v243 offset:50688
	global_load_lds_dwordx4 v223, s[4:5]
	v_mfma_f32_32x32x16_bf16 v[16:31], v[164:167], v[120:123], v[16:31]
	s_add_i32 m0, s21, 0xc000
	v_cndmask_b32_e64 v93, v93, v241, s[30:31]
	v_cmp_gt_i32_e64 s[30:31], 32, v242
	v_cndmask_b32_e64 v94, v94, v241, s[34:35]
	v_cmp_gt_i32_e64 s[34:35], 33, v242
	v_cndmask_b32_e64 v95, v95, v241, s[28:29]
	v_cmp_gt_i32_e64 s[28:29], 34, v242
	v_cndmask_b32_e64 v96, v96, v241, s[30:31]
	v_cmp_gt_i32_e64 s[30:31], 35, v242
	v_cndmask_b32_e64 v97, v97, v241, s[34:35]
	v_cmp_gt_i32_e64 s[34:35], 40, v242
	ds_read_b64_tr_b16 v[120:121], v243 offset:54272
	ds_read_b64_tr_b16 v[122:123], v243 offset:54784
	global_load_lds_dwordx4 v224, s[4:5]
	s_add_u32 s4, s4, 0x20000
	s_addc_u32 s5, s5, 0
	s_waitcnt lgkmcnt(8)
	v_mfma_f32_32x32x16_bf16 v[0:15], v[168:171], v[124:127], v[0:15]
	v_cndmask_b32_e64 v98, v98, v241, s[28:29]
	v_cmp_gt_i32_e64 s[28:29], 41, v242
	v_cndmask_b32_e64 v99, v99, v241, s[30:31]
	v_cmp_gt_i32_e64 s[30:31], 42, v242
	v_cndmask_b32_e64 v100, v100, v241, s[34:35]
	v_cmp_gt_i32_e64 s[34:35], 43, v242
	v_cndmask_b32_e64 v101, v101, v241, s[28:29]
	v_cmp_gt_i32_e64 s[28:29], 48, v242
	v_cndmask_b32_e64 v102, v102, v241, s[30:31]
	v_cmp_gt_i32_e64 s[30:31], 49, v242
	ds_read_b64_tr_b16 v[124:125], v243 offset:51200
	ds_read_b64_tr_b16 v[126:127], v243 offset:51712
	v_mfma_f32_32x32x16_bf16 v[16:31], v[168:171], v[128:131], v[16:31]
	v_cndmask_b32_e64 v103, v103, v241, s[34:35]
	v_cmp_gt_i32_e64 s[34:35], 50, v242
	v_cndmask_b32_e64 v104, v104, v241, s[28:29]
	v_cmp_gt_i32_e64 s[28:29], 51, v242
	v_cndmask_b32_e64 v105, v105, v241, s[30:31]
	v_cmp_gt_i32_e64 s[30:31], 56, v242
	v_cndmask_b32_e64 v106, v106, v241, s[34:35]
	v_cmp_gt_i32_e64 s[34:35], 57, v242
	v_cndmask_b32_e64 v107, v107, v241, s[28:29]
	v_cmp_gt_i32_e64 s[28:29], 58, v242
	ds_read_b64_tr_b16 v[128:129], v243 offset:55296
	ds_read_b64_tr_b16 v[130:131], v243 offset:55808
	v_mfma_f32_32x32x16_bf16 v[0:15], v[172:175], v[132:135], v[0:15]
	v_cndmask_b32_e64 v108, v108, v241, s[30:31]
	v_cmp_gt_i32_e64 s[30:31], 59, v242
	v_cndmask_b32_e64 v109, v109, v241, s[34:35]
	v_cndmask_b32_e64 v110, v110, v241, s[28:29]
	v_cndmask_b32_e64 v111, v111, v241, s[30:31]
	v_max3_f32 v246, v80, v81, v82
	v_max3_f32 v247, v83, v84, v85
	v_max3_f32 v246, v246, v86, v87
	v_max3_f32 v247, v247, v88, v89
	v_max3_f32 v246, v246, v90, v91
	ds_read_b64_tr_b16 v[132:133], v243 offset:52224
	ds_read_b64_tr_b16 v[134:135], v243 offset:52736
	v_mfma_f32_32x32x16_bf16 v[16:31], v[172:175], v[136:139], v[16:31]
	v_max3_f32 v247, v247, v92, v93
	v_max3_f32 v246, v246, v94, v95
	v_max3_f32 v247, v247, v96, v97
	v_max3_f32 v246, v246, v98, v99
	v_max3_f32 v247, v247, v100, v101
	v_max3_f32 v246, v246, v102, v103
	v_max3_f32 v247, v247, v104, v105
	v_max3_f32 v246, v246, v106, v107
	v_max3_f32 v247, v247, v108, v109
	v_max3_f32 v246, v246, v110, v111
	ds_read_b64_tr_b16 v[136:137], v243 offset:56320
	ds_read_b64_tr_b16 v[138:139], v243 offset:56832
	s_waitcnt lgkmcnt(8)
	v_mfma_f32_32x32x16_bf16 v[32:47], v[160:163], v[214:217], v[32:47]
	v_max_f32_e32 v248, v246, v247
	ds_read_b128 v[176:179], v244 offset:0
	ds_read_b128 v[180:183], v244 offset:512
	v_cmp_lt_f32_e32 vcc, s87, v248
	s_cbranch_vccnz .Lat_rare_T2

.Lat_T2_end:
.Lat_step_T1:
	s_cmp_lt_u32 s55, 3
	s_cbranch_scc1 .Lat_T1_light
	v_add_u32_e32 v243, s16, v204
	ds_read_b64_tr_b16 v[214:215], v243 offset:24576
	ds_read_b64_tr_b16 v[216:217], v243 offset:25088
	v_mfma_f32_32x32x16_bf16 v[112:127], v[176:179], v[144:147], v[64:79]
	v_add_f32_e32 v245, v80, v81
	v_add_f32_e32 v246, v82, v83
	v_add_f32_e32 v245, v84, v245
	v_add_f32_e32 v246, v85, v246
	v_cvt_pk_bf16_f32 v160, v80, v81
	v_cvt_pk_bf16_f32 v161, v82, v83
	ds_read_b64_tr_b16 v[80:81], v243 offset:28672
	ds_read_b64_tr_b16 v[82:83], v243 offset:29184
	v_mfma_f32_32x32x16_bf16 v[112:127], v[184:187], v[148:151], v[112:127]
	v_add_f32_e32 v245, v86, v245
	v_add_f32_e32 v246, v87, v246
	v_add_f32_e32 v245, v88, v245
	v_add_f32_e32 v246, v89, v246
	v_cvt_pk_bf16_f32 v162, v84, v85
	v_cvt_pk_bf16_f32 v163, v86, v87
	ds_read_b64_tr_b16 v[84:85], v243 offset:25600
	ds_read_b64_tr_b16 v[86:87], v243 offset:26112
	v_mfma_f32_32x32x16_bf16 v[112:127], v[192:195], v[152:155], v[112:127]
	v_add_f32_e32 v245, v90, v245
	v_add_f32_e32 v246, v91, v246
	v_add_f32_e32 v245, v92, v245
	v_add_f32_e32 v246, v93, v246
	v_cvt_pk_bf16_f32 v164, v88, v89
	v_cvt_pk_bf16_f32 v165, v90, v91
	ds_read_b64_tr_b16 v[88:89], v243 offset:29696
	ds_read_b64_tr_b16 v[90:91], v243 offset:30208
	v_mfma_f32_32x32x16_bf16 v[112:127], v[200:203], v[156:159], v[112:127]
	v_add_f32_e32 v245, v94, v245
	v_add_f32_e32 v246, v95, v246
	v_add_f32_e32 v245, v96, v245
	v_add_f32_e32 v246, v97, v246
	v_cvt_pk_bf16_f32 v166, v92, v93
	v_cvt_pk_bf16_f32 v167, v94, v95
	ds_read_b64_tr_b16 v[92:93], v243 offset:26624
	ds_read_b64_tr_b16 v[94:95], v243 offset:27136
	v_mfma_f32_32x32x16_bf16 v[128:143], v[180:183], v[144:147], v[64:79]
	v_add_f32_e32 v245, v98, v245
	v_add_f32_e32 v246, v99, v246
	v_add_f32_e32 v245, v100, v245
	v_add_f32_e32 v246, v101, v246
	v_cvt_pk_bf16_f32 v168, v96, v97
	v_cvt_pk_bf16_f32 v169, v98, v99
	ds_read_b64_tr_b16 v[96:97], v243 offset:30720
	ds_read_b64_tr_b16 v[98:99], v243 offset:31232
	v_mfma_f32_32x32x16_bf16 v[128:143], v[188:191], v[148:151], v[128:143]
	v_add_f32_e32 v245, v102, v245
	v_add_f32_e32 v246, v103, v246
	v_add_f32_e32 v245, v104, v245
	v_add_f32_e32 v246, v105, v246
	v_cvt_pk_bf16_f32 v170, v100, v101
	v_cvt_pk_bf16_f32 v171, v102, v103
	ds_read_b64_tr_b16 v[100:101], v243 offset:27648
	ds_read_b64_tr_b16 v[102:103], v243 offset:28160
	v_mfma_f32_32x32x16_bf16 v[128:143], v[196:199], v[152:155], v[128:143]
	v_add_f32_e32 v245, v106, v245
	v_add_f32_e32 v246, v107, v246
	v_add_f32_e32 v245, v108, v245
	v_add_f32_e32 v246, v109, v246
	v_cvt_pk_bf16_f32 v172, v104, v105
	v_cvt_pk_bf16_f32 v173, v106, v107
	ds_read_b64_tr_b16 v[104:105], v243 offset:31744
	ds_read_b64_tr_b16 v[106:107], v243 offset:32256
	v_mfma_f32_32x32x16_bf16 v[128:143], v[206:209], v[156:159], v[128:143]
	v_add_f32_e32 v245, v110, v245
	v_add_f32_e32 v246, v111, v246
	v_add_f32_e32 v245, v245, v246
	v_cvt_pk_bf16_f32 v174, v108, v109
	v_cvt_pk_bf16_f32 v175, v110, v111
	v_add_f32_e32 v211, v211, v245
	s_waitcnt lgkmcnt(8)
; __device__ __forceinline__ void cmask(f32x16&p0,f32x16&p1,int jb,int qrel,int hi){
;   const float NEG=-INFINITY; int kb=64*jb+4*hi;
;   #pragma unroll
;   for(int r=0;r<16;++r){int kv=kb+(r&3)+8*(r>>2); if(kv>qrel)p0[r]=NEG; if(kv+32>qrel)p1[r]=NEG;}
; }
	v_mfma_f32_32x32x16_bf16 v[0:15], v[160:163], v[214:217], v[0:15]
	v_add_u32_e32 v242, 0xffffff40, v225
	v_cmp_gt_i32_e64 s[28:29], 0, v242
	v_cmp_gt_i32_e64 s[30:31], 1, v242
	v_cmp_gt_i32_e64 s[34:35], 2, v242
	v_cndmask_b32_e64 v112, v112, v241, s[28:29]
	v_cmp_gt_i32_e64 s[28:29], 3, v242
	v_cndmask_b32_e64 v113, v113, v241, s[30:31]
	v_cmp_gt_i32_e64 s[30:31], 8, v242
	v_cndmask_b32_e64 v114, v114, v241, s[34:35]
	v_cmp_gt_i32_e64 s[34:35], 9, v242
	ds_read_b64_tr_b16 v[214:215], v243 offset:49152
	ds_read_b64_tr_b16 v[216:217], v243 offset:49664
	v_mfma_f32_32x32x16_bf16 v[16:31], v[160:163], v[80:83], v[16:31]
	v_cndmask_b32_e64 v115, v115, v241, s[28:29]
	v_cmp_gt_i32_e64 s[28:29], 10, v242
	v_cndmask_b32_e64 v116, v116, v241, s[30:31]
	v_cmp_gt_i32_e64 s[30:31], 11, v242
	v_cndmask_b32_e64 v117, v117, v241, s[34:35]
	v_cmp_gt_i32_e64 s[34:35], 16, v242
	v_cndmask_b32_e64 v118, v118, v241, s[28:29]
	v_cmp_gt_i32_e64 s[28:29], 17, v242
	v_cndmask_b32_e64 v119, v119, v241, s[30:31]
	v_cmp_gt_i32_e64 s[30:31], 18, v242
	ds_read_b64_tr_b16 v[80:81], v243 offset:53248
	ds_read_b64_tr_b16 v[82:83], v243 offset:53760
	v_mfma_f32_32x32x16_bf16 v[0:15], v[164:167], v[84:87], v[0:15]
	v_cndmask_b32_e64 v120, v120, v241, s[34:35]
	v_cmp_gt_i32_e64 s[34:35], 19, v242
	v_cndmask_b32_e64 v121, v121, v241, s[28:29]
	v_cmp_gt_i32_e64 s[28:29], 24, v242
	v_cndmask_b32_e64 v122, v122, v241, s[30:31]
	v_cmp_gt_i32_e64 s[30:31], 25, v242
	v_cndmask_b32_e64 v123, v123, v241, s[34:35]
	v_cmp_gt_i32_e64 s[34:35], 26, v242
	v_cndmask_b32_e64 v124, v124, v241, s[28:29]
	v_cmp_gt_i32_e64 s[28:29], 27, v242
	ds_read_b64_tr_b16 v[84:85], v243 offset:50176
	ds_read_b64_tr_b16 v[86:87], v243 offset:50688
	v_mfma_f32_32x32x16_bf16 v[16:31], v[164:167], v[88:91], v[16:31]
	v_cndmask_b32_e64 v125, v125, v241, s[30:31]
	v_cmp_gt_i32_e64 s[30:31], 32, v242
	v_cndmask_b32_e64 v126, v126, v241, s[34:35]
	v_cmp_gt_i32_e64 s[34:35], 33, v242
	v_cndmask_b32_e64 v127, v127, v241, s[28:29]
	v_cmp_gt_i32_e64 s[28:29], 34, v242
	v_cndmask_b32_e64 v128, v128, v241, s[30:31]
	v_cmp_gt_i32_e64 s[30:31], 35, v242
	v_cndmask_b32_e64 v129, v129, v241, s[34:35]
	v_cmp_gt_i32_e64 s[34:35], 40, v242
	ds_read_b64_tr_b16 v[88:89], v243 offset:54272
	ds_read_b64_tr_b16 v[90:91], v243 offset:54784
	s_waitcnt lgkmcnt(8)
	v_mfma_f32_32x32x16_bf16 v[0:15], v[168:171], v[92:95], v[0:15]
	v_cndmask_b32_e64 v130, v130, v241, s[28:29]
	v_cmp_gt_i32_e64 s[28:29], 41, v242
	v_cndmask_b32_e64 v131, v131, v241, s[30:31]
	v_cmp_gt_i32_e64 s[30:31], 42, v242
	v_cndmask_b32_e64 v132, v132, v241, s[34:35]
	v_cmp_gt_i32_e64 s[34:35], 43, v242
	v_cndmask_b32_e64 v133, v133, v241, s[28:29]
	v_cmp_gt_i32_e64 s[28:29], 48, v242
	v_cndmask_b32_e64 v134, v134, v241, s[30:31]
	v_cmp_gt_i32_e64 s[30:31], 49, v242
	ds_read_b64_tr_b16 v[92:93], v243 offset:51200
	ds_read_b64_tr_b16 v[94:95], v243 offset:51712
	v_mfma_f32_32x32x16_bf16 v[16:31], v[168:171], v[96:99], v[16:31]
	v_cndmask_b32_e64 v135, v135, v241, s[34:35]
	v_cmp_gt_i32_e64 s[34:35], 50, v242
	v_cndmask_b32_e64 v136, v136, v241, s[28:29]
	v_cmp_gt_i32_e64 s[28:29], 51, v242
	v_cndmask_b32_e64 v137, v137, v241, s[30:31]
	v_cmp_gt_i32_e64 s[30:31], 56, v242
	v_cndmask_b32_e64 v138, v138, v241, s[34:35]
	v_cmp_gt_i32_e64 s[34:35], 57, v242
	v_cndmask_b32_e64 v139, v139, v241, s[28:29]
	v_cmp_gt_i32_e64 s[28:29], 58, v242
	ds_read_b64_tr_b16 v[96:97], v243 offset:55296
	ds_read_b64_tr_b16 v[98:99], v243 offset:55808
	v_mfma_f32_32x32x16_bf16 v[0:15], v[172:175], v[100:103], v[0:15]
	v_cndmask_b32_e64 v140, v140, v241, s[30:31]
	v_cmp_gt_i32_e64 s[30:31], 59, v242
	v_cndmask_b32_e64 v141, v141, v241, s[34:35]
	v_cndmask_b32_e64 v142, v142, v241, s[28:29]
	v_cndmask_b32_e64 v143, v143, v241, s[30:31]
	v_max3_f32 v246, v112, v113, v114
	v_max3_f32 v247, v115, v116, v117
	v_max3_f32 v246, v246, v118, v119
	v_max3_f32 v247, v247, v120, v121
	v_max3_f32 v246, v246, v122, v123
	ds_read_b64_tr_b16 v[100:101], v243 offset:52224
	ds_read_b64_tr_b16 v[102:103], v243 offset:52736
	v_mfma_f32_32x32x16_bf16 v[16:31], v[172:175], v[104:107], v[16:31]
	v_max3_f32 v247, v247, v124, v125
	v_max3_f32 v246, v246, v126, v127
	v_max3_f32 v247, v247, v128, v129
	v_max3_f32 v246, v246, v130, v131
	v_max3_f32 v247, v247, v132, v133
	v_max3_f32 v246, v246, v134, v135
	v_max3_f32 v247, v247, v136, v137
	v_max3_f32 v246, v246, v138, v139
	v_max3_f32 v247, v247, v140, v141
	v_max3_f32 v246, v246, v142, v143
	ds_read_b64_tr_b16 v[104:105], v243 offset:56320
	ds_read_b64_tr_b16 v[106:107], v243 offset:56832
	s_waitcnt lgkmcnt(8)
	v_mfma_f32_32x32x16_bf16 v[32:47], v[160:163], v[214:217], v[32:47]
	v_max_f32_e32 v248, v246, v247
	v_cmp_lt_f32_e32 vcc, s87, v248
	s_cbranch_vccnz .Lat_rare_T1
